# lever9: K-loop head SALU block moved behind the first load segment's ds_reads/DMA issue, loop counter and pointer steps moved in front of the loop-back barrier (only the branch follows it)
# baseline (speedup 1.0000x reference)
.LBB0_405:
	ds_read_b128 v[0:3], v253
	ds_read_b128 v[4:7], v253 offset:1024
	ds_read_b128 v[138:141], v253 offset:2048
	ds_read_b128 v[142:145], v253 offset:3072
	ds_read_b128 v[146:149], v253 offset:16384
	ds_read_b128 v[150:153], v253 offset:17408
	ds_read_b128 v[180:183], v253 offset:18432
	ds_read_b128 v[184:187], v253 offset:19456
	s_add_i32 m0, s69, 0xc000
	ds_read_b128 v[188:191], v231
	ds_read_b128 v[192:195], v231 offset:1024
	ds_read_b128 v[196:199], v231 offset:2048
	ds_read_b128 v[200:203], v231 offset:3072
	ds_read_b128 v[204:207], v231 offset:4096
	ds_read_b128 v[234:237], v231 offset:5120
	ds_read_b128 v[238:241], v231 offset:6144
	ds_read_b128 v[242:245], v231 offset:7168
	global_load_lds_dwordx4 v166, s[2:3]
	s_add_i32 m0, s69, 0xe000
	s_nop 0
	global_load_lds_dwordx4 v168, s[2:3]
	s_add_u32 s12, s2, 0xfffc0080
	s_addc_u32 s13, s3, -1
	s_add_i32 s23, 0, 0x10000
	s_cmp_eq_u32 s22, 12
	s_cselect_b32 s15, s16, s13
	s_cselect_b32 s14, s17, s12
	s_cselect_b32 s13, s18, s21
	s_cselect_b32 s12, s19, s20
	s_add_i32 s31, 0, 0x14000
	s_waitcnt vmcnt(8)
	s_waitcnt lgkmcnt(0)
	s_barrier
	s_setprio 1
	s_waitcnt lgkmcnt(0)
	v_mfma_f32_16x16x32_bf16 v[134:137], v[0:3], v[188:191], v[134:137]
	v_mfma_f32_16x16x32_bf16 v[130:133], v[138:141], v[188:191], v[130:133]
	v_mfma_f32_16x16x32_bf16 v[118:121], v[0:3], v[196:199], v[118:121]
	v_mfma_f32_16x16x32_bf16 v[114:117], v[138:141], v[196:199], v[114:117]
	v_mfma_f32_16x16x32_bf16 v[102:105], v[0:3], v[204:207], v[102:105]
	v_mfma_f32_16x16x32_bf16 v[98:101], v[138:141], v[204:207], v[98:101]
	v_mfma_f32_16x16x32_bf16 v[84:87], v[0:3], v[238:241], v[84:87]
	v_mfma_f32_16x16x32_bf16 v[80:83], v[138:141], v[238:241], v[80:83]
	v_mfma_f32_16x16x32_bf16 v[134:137], v[4:7], v[192:195], v[134:137]
	v_mfma_f32_16x16x32_bf16 v[130:133], v[142:145], v[192:195], v[130:133]
	v_mfma_f32_16x16x32_bf16 v[118:121], v[4:7], v[200:203], v[118:121]
	v_mfma_f32_16x16x32_bf16 v[114:117], v[142:145], v[200:203], v[114:117]
	v_mfma_f32_16x16x32_bf16 v[102:105], v[4:7], v[234:237], v[102:105]
	v_mfma_f32_16x16x32_bf16 v[98:101], v[142:145], v[234:237], v[98:101]
	v_mfma_f32_16x16x32_bf16 v[84:87], v[4:7], v[242:245], v[84:87]
	v_mfma_f32_16x16x32_bf16 v[80:83], v[142:145], v[242:245], v[80:83]
	s_setprio 0
	s_setprio 1
	v_mfma_f32_16x16x32_bf16 v[126:129], v[146:149], v[188:191], v[126:129]
	v_mfma_f32_16x16x32_bf16 v[122:125], v[180:183], v[188:191], v[122:125]
	v_mfma_f32_16x16x32_bf16 v[110:113], v[146:149], v[196:199], v[110:113]
	v_mfma_f32_16x16x32_bf16 v[106:109], v[180:183], v[196:199], v[106:109]
	v_mfma_f32_16x16x32_bf16 v[92:95], v[146:149], v[204:207], v[92:95]
	v_mfma_f32_16x16x32_bf16 v[88:91], v[180:183], v[204:207], v[88:91]
	v_mfma_f32_16x16x32_bf16 v[76:79], v[146:149], v[238:241], v[76:79]
	v_mfma_f32_16x16x32_bf16 v[72:75], v[180:183], v[238:241], v[72:75]
	v_mfma_f32_16x16x32_bf16 v[126:129], v[150:153], v[192:195], v[126:129]
	v_mfma_f32_16x16x32_bf16 v[122:125], v[184:187], v[192:195], v[122:125]
	v_mfma_f32_16x16x32_bf16 v[110:113], v[150:153], v[200:203], v[110:113]
	v_mfma_f32_16x16x32_bf16 v[106:109], v[184:187], v[200:203], v[106:109]
	v_mfma_f32_16x16x32_bf16 v[92:95], v[150:153], v[234:237], v[92:95]
	v_mfma_f32_16x16x32_bf16 v[88:91], v[184:187], v[234:237], v[88:91]
	v_mfma_f32_16x16x32_bf16 v[76:79], v[150:153], v[242:245], v[76:79]
	v_mfma_f32_16x16x32_bf16 v[72:75], v[184:187], v[242:245], v[72:75]
	s_setprio 0
	s_barrier
	s_add_i32 s23, s23, s58
	s_mov_b32 m0, s23
	ds_read_b128 v[188:191], v231 offset:16384
	ds_read_b128 v[192:195], v231 offset:17408
	ds_read_b128 v[196:199], v231 offset:18432
	ds_read_b128 v[200:203], v231 offset:19456
	ds_read_b128 v[204:207], v231 offset:20480
	ds_read_b128 v[234:237], v231 offset:21504
	ds_read_b128 v[238:241], v231 offset:22528
	ds_read_b128 v[242:245], v231 offset:23552
	global_load_lds_dwordx4 v156, s[12:13]
	s_add_i32 m0, s23, 0x2000
	s_add_u32 s26, s12, 0x10000
	s_addc_u32 s27, s13, 0
	s_add_i32 s23, s31, s58
	global_load_lds_dwordx4 v160, s[12:13]
	s_mov_b32 m0, s23
	s_nop 0
	global_load_lds_dwordx4 v156, s[26:27]
	s_add_i32 m0, s23, 0x2000
	s_nop 0
	global_load_lds_dwordx4 v160, s[26:27]
	s_mov_b64 s[26:27], s[14:15]
	s_mov_b32 m0, s69
	s_nop 0
	global_load_lds_dwordx4 v154, s[14:15]
	s_mov_b32 m0, s70
	s_nop 0
	global_load_lds_dwordx4 v158, s[14:15]
	s_waitcnt vmcnt(8)
	s_waitcnt lgkmcnt(0)
	s_barrier
	s_setprio 1
	s_waitcnt lgkmcnt(0)
	v_mfma_f32_16x16x32_bf16 v[68:71], v[0:3], v[188:191], v[68:71]
	v_mfma_f32_16x16x32_bf16 v[64:67], v[138:141], v[188:191], v[64:67]
	v_mfma_f32_16x16x32_bf16 v[52:55], v[0:3], v[196:199], v[52:55]
	v_mfma_f32_16x16x32_bf16 v[48:51], v[138:141], v[196:199], v[48:51]
	v_mfma_f32_16x16x32_bf16 v[36:39], v[0:3], v[204:207], v[36:39]
	v_mfma_f32_16x16x32_bf16 v[32:35], v[138:141], v[204:207], v[32:35]
	v_mfma_f32_16x16x32_bf16 v[0:3], v[0:3], v[238:241], v[20:23]
	v_mfma_f32_16x16x32_bf16 v[68:71], v[4:7], v[192:195], v[68:71]
	v_mfma_f32_16x16x32_bf16 v[64:67], v[142:145], v[192:195], v[64:67]
	v_mfma_f32_16x16x32_bf16 v[52:55], v[4:7], v[200:203], v[52:55]
	v_mfma_f32_16x16x32_bf16 v[48:51], v[142:145], v[200:203], v[48:51]
	v_mfma_f32_16x16x32_bf16 v[36:39], v[4:7], v[234:237], v[36:39]
	v_mfma_f32_16x16x32_bf16 v[32:35], v[142:145], v[234:237], v[32:35]
	v_mfma_f32_16x16x32_bf16 v[0:3], v[4:7], v[242:245], v[0:3]
	v_mfma_f32_16x16x32_bf16 v[4:7], v[138:141], v[238:241], v[16:19]
	v_mfma_f32_16x16x32_bf16 v[4:7], v[142:145], v[242:245], v[4:7]
	s_setprio 0
	s_setprio 1
	v_mfma_f32_16x16x32_bf16 v[16:19], v[146:149], v[188:191], v[60:63]
	v_mfma_f32_16x16x32_bf16 v[60:63], v[150:153], v[192:195], v[16:19]
	v_mfma_f32_16x16x32_bf16 v[16:19], v[180:183], v[188:191], v[56:59]
	v_mfma_f32_16x16x32_bf16 v[56:59], v[184:187], v[192:195], v[16:19]
	v_mfma_f32_16x16x32_bf16 v[16:19], v[146:149], v[196:199], v[44:47]
	v_mfma_f32_16x16x32_bf16 v[44:47], v[150:153], v[200:203], v[16:19]
	v_mfma_f32_16x16x32_bf16 v[16:19], v[180:183], v[196:199], v[40:43]
	v_mfma_f32_16x16x32_bf16 v[40:43], v[184:187], v[200:203], v[16:19]
	v_mfma_f32_16x16x32_bf16 v[16:19], v[146:149], v[204:207], v[28:31]
	v_mfma_f32_16x16x32_bf16 v[28:31], v[150:153], v[234:237], v[16:19]
	v_mfma_f32_16x16x32_bf16 v[16:19], v[180:183], v[204:207], v[24:27]
	v_mfma_f32_16x16x32_bf16 v[12:15], v[146:149], v[238:241], v[12:15]
	v_mfma_f32_16x16x32_bf16 v[8:11], v[180:183], v[238:241], v[8:11]
	v_mfma_f32_16x16x32_bf16 v[24:27], v[184:187], v[234:237], v[16:19]
	v_mfma_f32_16x16x32_bf16 v[12:15], v[150:153], v[242:245], v[12:15]
	v_mfma_f32_16x16x32_bf16 v[8:11], v[184:187], v[242:245], v[8:11]
	s_setprio 0
	s_barrier
	s_add_i32 s23, 0, 0x1c000
	ds_read_b128 v[16:19], v253 offset:32768
	ds_read_b128 v[20:23], v253 offset:33792
	ds_read_b128 v[138:141], v253 offset:34816
	ds_read_b128 v[142:145], v253 offset:35840
	ds_read_b128 v[146:149], v253 offset:49152
	ds_read_b128 v[150:153], v253 offset:50176
	ds_read_b128 v[180:183], v253 offset:51200
	ds_read_b128 v[184:187], v253 offset:52224
	s_add_u32 s14, s14, 0x40000
	s_addc_u32 s15, s15, 0
	s_mov_b32 m0, s71
	ds_read_b128 v[188:191], v231 offset:32768
	ds_read_b128 v[192:195], v231 offset:33792
	ds_read_b128 v[196:199], v231 offset:34816
	ds_read_b128 v[200:203], v231 offset:35840
	ds_read_b128 v[204:207], v231 offset:36864
	ds_read_b128 v[234:237], v231 offset:37888
	ds_read_b128 v[238:241], v231 offset:38912
	ds_read_b128 v[242:245], v231 offset:39936
	global_load_lds_dwordx4 v154, s[14:15]
	s_mov_b32 m0, s76
	s_nop 0
	global_load_lds_dwordx4 v158, s[14:15]
	s_waitcnt vmcnt(8)
	s_waitcnt lgkmcnt(0)
	s_barrier
	s_setprio 1
	s_waitcnt lgkmcnt(0)
	v_mfma_f32_16x16x32_bf16 v[134:137], v[16:19], v[188:191], v[134:137]
	v_mfma_f32_16x16x32_bf16 v[130:133], v[138:141], v[188:191], v[130:133]
	v_mfma_f32_16x16x32_bf16 v[118:121], v[16:19], v[196:199], v[118:121]
	v_mfma_f32_16x16x32_bf16 v[114:117], v[138:141], v[196:199], v[114:117]
	v_mfma_f32_16x16x32_bf16 v[102:105], v[16:19], v[204:207], v[102:105]
	v_mfma_f32_16x16x32_bf16 v[98:101], v[138:141], v[204:207], v[98:101]
	v_mfma_f32_16x16x32_bf16 v[84:87], v[16:19], v[238:241], v[84:87]
	v_mfma_f32_16x16x32_bf16 v[80:83], v[138:141], v[238:241], v[80:83]
	v_mfma_f32_16x16x32_bf16 v[134:137], v[20:23], v[192:195], v[134:137]
	v_mfma_f32_16x16x32_bf16 v[130:133], v[142:145], v[192:195], v[130:133]
	v_mfma_f32_16x16x32_bf16 v[118:121], v[20:23], v[200:203], v[118:121]
	v_mfma_f32_16x16x32_bf16 v[114:117], v[142:145], v[200:203], v[114:117]
	v_mfma_f32_16x16x32_bf16 v[102:105], v[20:23], v[234:237], v[102:105]
	v_mfma_f32_16x16x32_bf16 v[98:101], v[142:145], v[234:237], v[98:101]
	v_mfma_f32_16x16x32_bf16 v[84:87], v[20:23], v[242:245], v[84:87]
	v_mfma_f32_16x16x32_bf16 v[80:83], v[142:145], v[242:245], v[80:83]
	s_setprio 0
	s_setprio 1
	v_mfma_f32_16x16x32_bf16 v[126:129], v[146:149], v[188:191], v[126:129]
	v_mfma_f32_16x16x32_bf16 v[122:125], v[180:183], v[188:191], v[122:125]
	v_mfma_f32_16x16x32_bf16 v[110:113], v[146:149], v[196:199], v[110:113]
	v_mfma_f32_16x16x32_bf16 v[106:109], v[180:183], v[196:199], v[106:109]
	v_mfma_f32_16x16x32_bf16 v[92:95], v[146:149], v[204:207], v[92:95]
	v_mfma_f32_16x16x32_bf16 v[88:91], v[180:183], v[204:207], v[88:91]
	v_mfma_f32_16x16x32_bf16 v[76:79], v[146:149], v[238:241], v[76:79]
	v_mfma_f32_16x16x32_bf16 v[72:75], v[180:183], v[238:241], v[72:75]
	v_mfma_f32_16x16x32_bf16 v[126:129], v[150:153], v[192:195], v[126:129]
	v_mfma_f32_16x16x32_bf16 v[122:125], v[184:187], v[192:195], v[122:125]
	v_mfma_f32_16x16x32_bf16 v[110:113], v[150:153], v[200:203], v[110:113]
	v_mfma_f32_16x16x32_bf16 v[106:109], v[184:187], v[200:203], v[106:109]
	v_mfma_f32_16x16x32_bf16 v[92:95], v[150:153], v[234:237], v[92:95]
	v_mfma_f32_16x16x32_bf16 v[88:91], v[184:187], v[234:237], v[88:91]
	v_mfma_f32_16x16x32_bf16 v[76:79], v[150:153], v[242:245], v[76:79]
	v_mfma_f32_16x16x32_bf16 v[72:75], v[184:187], v[242:245], v[72:75]
	s_setprio 0
	s_barrier
	s_add_i32 s14, s67, s58
	s_add_i32 m0, s14, 0xffffff80
	ds_read_b128 v[188:191], v231 offset:49152
	ds_read_b128 v[192:195], v231 offset:50176
	ds_read_b128 v[196:199], v231 offset:51200
	ds_read_b128 v[200:203], v231 offset:52224
	ds_read_b128 v[204:207], v231 offset:53248
	ds_read_b128 v[234:237], v231 offset:54272
	ds_read_b128 v[238:241], v231 offset:55296
	ds_read_b128 v[242:245], v231 offset:56320
	global_load_lds_dwordx4 v156, s[12:13] offset:128
	s_add_i32 m0, s14, 0x1f80
	s_add_i32 s14, s23, s58
	global_load_lds_dwordx4 v160, s[12:13] offset:128
	s_add_u32 s12, s12, 0x10080
	s_addc_u32 s13, s13, 0
	s_mov_b32 m0, s14
	s_nop 0
	global_load_lds_dwordx4 v156, s[12:13]
	s_add_i32 m0, s14, 0x2000
	s_nop 0
	global_load_lds_dwordx4 v160, s[12:13]
	s_add_i32 m0, s96, 0xffffff80
	s_nop 0
	global_load_lds_dwordx4 v154, s[26:27] offset:128
	s_add_i32 m0, s36, 0xffffff80
	s_nop 0
	global_load_lds_dwordx4 v158, s[26:27] offset:128
	s_waitcnt vmcnt(8)
	s_waitcnt lgkmcnt(0)
	s_barrier
	s_setprio 1
	s_waitcnt lgkmcnt(0)
	v_mfma_f32_16x16x32_bf16 v[68:71], v[16:19], v[188:191], v[68:71]
	v_mfma_f32_16x16x32_bf16 v[52:55], v[16:19], v[196:199], v[52:55]
	v_mfma_f32_16x16x32_bf16 v[36:39], v[16:19], v[204:207], v[36:39]
	v_mfma_f32_16x16x32_bf16 v[0:3], v[16:19], v[238:241], v[0:3]
	v_mfma_f32_16x16x32_bf16 v[68:71], v[20:23], v[192:195], v[68:71]
	v_mfma_f32_16x16x32_bf16 v[64:67], v[138:141], v[188:191], v[64:67]
	v_mfma_f32_16x16x32_bf16 v[52:55], v[20:23], v[200:203], v[52:55]
	v_mfma_f32_16x16x32_bf16 v[48:51], v[138:141], v[196:199], v[48:51]
	v_mfma_f32_16x16x32_bf16 v[36:39], v[20:23], v[234:237], v[36:39]
	v_mfma_f32_16x16x32_bf16 v[32:35], v[138:141], v[204:207], v[32:35]
	v_mfma_f32_16x16x32_bf16 v[20:23], v[20:23], v[242:245], v[0:3]
	v_mfma_f32_16x16x32_bf16 v[0:3], v[138:141], v[238:241], v[4:7]
	v_mfma_f32_16x16x32_bf16 v[64:67], v[142:145], v[192:195], v[64:67]
	v_mfma_f32_16x16x32_bf16 v[48:51], v[142:145], v[200:203], v[48:51]
	v_mfma_f32_16x16x32_bf16 v[32:35], v[142:145], v[234:237], v[32:35]
	v_mfma_f32_16x16x32_bf16 v[16:19], v[142:145], v[242:245], v[0:3]
	s_setprio 0
	s_setprio 1
	v_mfma_f32_16x16x32_bf16 v[0:3], v[146:149], v[188:191], v[60:63]
	v_mfma_f32_16x16x32_bf16 v[60:63], v[150:153], v[192:195], v[0:3]
	v_mfma_f32_16x16x32_bf16 v[0:3], v[180:183], v[188:191], v[56:59]
	v_mfma_f32_16x16x32_bf16 v[56:59], v[184:187], v[192:195], v[0:3]
	v_mfma_f32_16x16x32_bf16 v[0:3], v[146:149], v[196:199], v[44:47]
	v_mfma_f32_16x16x32_bf16 v[44:47], v[150:153], v[200:203], v[0:3]
	v_mfma_f32_16x16x32_bf16 v[0:3], v[180:183], v[196:199], v[40:43]
	v_mfma_f32_16x16x32_bf16 v[40:43], v[184:187], v[200:203], v[0:3]
	v_mfma_f32_16x16x32_bf16 v[0:3], v[146:149], v[204:207], v[28:31]
	v_mfma_f32_16x16x32_bf16 v[28:31], v[150:153], v[234:237], v[0:3]
	v_mfma_f32_16x16x32_bf16 v[0:3], v[180:183], v[204:207], v[24:27]
	v_mfma_f32_16x16x32_bf16 v[24:27], v[184:187], v[234:237], v[0:3]
	v_mfma_f32_16x16x32_bf16 v[0:3], v[146:149], v[238:241], v[12:15]
	v_mfma_f32_16x16x32_bf16 v[12:15], v[150:153], v[242:245], v[0:3]
	v_mfma_f32_16x16x32_bf16 v[0:3], v[180:183], v[238:241], v[8:11]
	v_mfma_f32_16x16x32_bf16 v[8:11], v[184:187], v[242:245], v[0:3]
	s_setprio 0
	s_add_i32 s22, s22, 2
	s_add_u32 s2, s2, 0x100
	s_addc_u32 s3, s3, 0
	s_add_u32 s20, s20, 0x100
	s_addc_u32 s21, s21, 0
	s_cmp_gt_u32 s22, 13
	s_barrier
	s_cbranch_scc0 .LBB0_405
	s_and_b64 vcc, exec, s[42:43]
	s_cbranch_vccz .LBB0_418
	s_barrier
	s_andn2_b64 vcc, exec, s[38:39]
	s_mov_b64 s[2:3], -1
	s_cbranch_vccz .LBB0_419

.LBB0_750:
	ds_read_b128 v[0:3], v253
	ds_read_b128 v[4:7], v253 offset:1024
	ds_read_b128 v[138:141], v253 offset:2048
	ds_read_b128 v[142:145], v253 offset:3072
	ds_read_b128 v[146:149], v253 offset:16384
	ds_read_b128 v[150:153], v253 offset:17408
	ds_read_b128 v[182:185], v253 offset:18432
	ds_read_b128 v[186:189], v253 offset:19456
	s_add_i32 m0, s79, 0xc000
	ds_read_b128 v[190:193], v221
	ds_read_b128 v[194:197], v221 offset:1024
	ds_read_b128 v[198:201], v221 offset:2048
	ds_read_b128 v[202:205], v221 offset:3072
	ds_read_b128 v[222:225], v221 offset:4096
	ds_read_b128 v[226:229], v221 offset:5120
	ds_read_b128 v[230:233], v221 offset:6144
	ds_read_b128 v[234:237], v221 offset:7168
	global_load_lds_dwordx4 v168, s[4:5]
	s_add_i32 m0, s79, 0xe000
	s_nop 0
	global_load_lds_dwordx4 v170, s[4:5]
	s_add_u32 s12, s4, 0xfffc0080
	s_addc_u32 s13, s5, -1
	s_add_i32 s33, 0, 0x10000
	s_cmp_eq_u32 s27, 12
	s_cselect_b32 s15, s3, s13
	s_cselect_b32 s14, s16, s12
	s_cselect_b32 s13, s17, s26
	s_cselect_b32 s12, s18, s19
	s_add_i32 s35, 0, 0x14000
	s_waitcnt vmcnt(8)
	s_waitcnt lgkmcnt(0)
	s_barrier
	s_setprio 1
	s_waitcnt lgkmcnt(0)
	v_mfma_f32_16x16x32_bf16 v[134:137], v[0:3], v[190:193], v[134:137]
	v_mfma_f32_16x16x32_bf16 v[130:133], v[138:141], v[190:193], v[130:133]
	v_mfma_f32_16x16x32_bf16 v[118:121], v[0:3], v[198:201], v[118:121]
	v_mfma_f32_16x16x32_bf16 v[114:117], v[138:141], v[198:201], v[114:117]
	v_mfma_f32_16x16x32_bf16 v[102:105], v[0:3], v[222:225], v[102:105]
	v_mfma_f32_16x16x32_bf16 v[98:101], v[138:141], v[222:225], v[98:101]
	v_mfma_f32_16x16x32_bf16 v[84:87], v[0:3], v[230:233], v[84:87]
	v_mfma_f32_16x16x32_bf16 v[80:83], v[138:141], v[230:233], v[80:83]
	v_mfma_f32_16x16x32_bf16 v[134:137], v[4:7], v[194:197], v[134:137]
	v_mfma_f32_16x16x32_bf16 v[130:133], v[142:145], v[194:197], v[130:133]
	v_mfma_f32_16x16x32_bf16 v[118:121], v[4:7], v[202:205], v[118:121]
	v_mfma_f32_16x16x32_bf16 v[114:117], v[142:145], v[202:205], v[114:117]
	v_mfma_f32_16x16x32_bf16 v[102:105], v[4:7], v[226:229], v[102:105]
	v_mfma_f32_16x16x32_bf16 v[98:101], v[142:145], v[226:229], v[98:101]
	v_mfma_f32_16x16x32_bf16 v[84:87], v[4:7], v[234:237], v[84:87]
	v_mfma_f32_16x16x32_bf16 v[80:83], v[142:145], v[234:237], v[80:83]
	s_setprio 0
	s_setprio 1
	v_mfma_f32_16x16x32_bf16 v[126:129], v[146:149], v[190:193], v[126:129]
	v_mfma_f32_16x16x32_bf16 v[122:125], v[182:185], v[190:193], v[122:125]
	v_mfma_f32_16x16x32_bf16 v[110:113], v[146:149], v[198:201], v[110:113]
	v_mfma_f32_16x16x32_bf16 v[106:109], v[182:185], v[198:201], v[106:109]
	v_mfma_f32_16x16x32_bf16 v[92:95], v[146:149], v[222:225], v[92:95]
	v_mfma_f32_16x16x32_bf16 v[88:91], v[182:185], v[222:225], v[88:91]
	v_mfma_f32_16x16x32_bf16 v[76:79], v[146:149], v[230:233], v[76:79]
	v_mfma_f32_16x16x32_bf16 v[72:75], v[182:185], v[230:233], v[72:75]
	v_mfma_f32_16x16x32_bf16 v[126:129], v[150:153], v[194:197], v[126:129]
	v_mfma_f32_16x16x32_bf16 v[122:125], v[186:189], v[194:197], v[122:125]
	v_mfma_f32_16x16x32_bf16 v[110:113], v[150:153], v[202:205], v[110:113]
	v_mfma_f32_16x16x32_bf16 v[106:109], v[186:189], v[202:205], v[106:109]
	v_mfma_f32_16x16x32_bf16 v[92:95], v[150:153], v[226:229], v[92:95]
	v_mfma_f32_16x16x32_bf16 v[88:91], v[186:189], v[226:229], v[88:91]
	v_mfma_f32_16x16x32_bf16 v[76:79], v[150:153], v[234:237], v[76:79]
	v_mfma_f32_16x16x32_bf16 v[72:75], v[186:189], v[234:237], v[72:75]
	s_setprio 0
	s_barrier
	s_add_i32 s33, s33, s78
	s_mov_b32 m0, s33
	ds_read_b128 v[190:193], v221 offset:16384
	ds_read_b128 v[194:197], v221 offset:17408
	ds_read_b128 v[198:201], v221 offset:18432
	ds_read_b128 v[202:205], v221 offset:19456
	ds_read_b128 v[222:225], v221 offset:20480
	ds_read_b128 v[226:229], v221 offset:21504
	ds_read_b128 v[230:233], v221 offset:22528
	ds_read_b128 v[234:237], v221 offset:23552
	global_load_lds_dwordx4 v156, s[12:13]
	s_add_i32 m0, s33, 0x2000
	s_add_u32 s42, s12, 0x10000
	s_addc_u32 s43, s13, 0
	s_add_i32 s33, s35, s78
	global_load_lds_dwordx4 v160, s[12:13]
	s_mov_b32 m0, s33
	s_nop 0
	global_load_lds_dwordx4 v156, s[42:43]
	s_add_i32 m0, s33, 0x2000
	s_nop 0
	global_load_lds_dwordx4 v160, s[42:43]
	s_mov_b64 s[42:43], s[14:15]
	s_mov_b32 m0, s79
	s_nop 0
	global_load_lds_dwordx4 v154, s[14:15]
	s_mov_b32 m0, s81
	s_nop 0
	global_load_lds_dwordx4 v158, s[14:15]
	s_waitcnt vmcnt(8)
	s_waitcnt lgkmcnt(0)
	s_barrier
	s_setprio 1
	s_waitcnt lgkmcnt(0)
	v_mfma_f32_16x16x32_bf16 v[68:71], v[0:3], v[190:193], v[68:71]
	v_mfma_f32_16x16x32_bf16 v[64:67], v[138:141], v[190:193], v[64:67]
	v_mfma_f32_16x16x32_bf16 v[52:55], v[0:3], v[198:201], v[52:55]
	v_mfma_f32_16x16x32_bf16 v[48:51], v[138:141], v[198:201], v[48:51]
	v_mfma_f32_16x16x32_bf16 v[36:39], v[0:3], v[222:225], v[36:39]
	v_mfma_f32_16x16x32_bf16 v[32:35], v[138:141], v[222:225], v[32:35]
	v_mfma_f32_16x16x32_bf16 v[0:3], v[0:3], v[230:233], v[20:23]
	v_mfma_f32_16x16x32_bf16 v[68:71], v[4:7], v[194:197], v[68:71]
	v_mfma_f32_16x16x32_bf16 v[64:67], v[142:145], v[194:197], v[64:67]
	v_mfma_f32_16x16x32_bf16 v[52:55], v[4:7], v[202:205], v[52:55]
	v_mfma_f32_16x16x32_bf16 v[48:51], v[142:145], v[202:205], v[48:51]
	v_mfma_f32_16x16x32_bf16 v[36:39], v[4:7], v[226:229], v[36:39]
	v_mfma_f32_16x16x32_bf16 v[32:35], v[142:145], v[226:229], v[32:35]
	v_mfma_f32_16x16x32_bf16 v[0:3], v[4:7], v[234:237], v[0:3]
	v_mfma_f32_16x16x32_bf16 v[4:7], v[138:141], v[230:233], v[16:19]
	v_mfma_f32_16x16x32_bf16 v[4:7], v[142:145], v[234:237], v[4:7]
	s_setprio 0
	s_setprio 1
	v_mfma_f32_16x16x32_bf16 v[16:19], v[146:149], v[190:193], v[60:63]
	v_mfma_f32_16x16x32_bf16 v[60:63], v[150:153], v[194:197], v[16:19]
	v_mfma_f32_16x16x32_bf16 v[16:19], v[182:185], v[190:193], v[56:59]
	v_mfma_f32_16x16x32_bf16 v[56:59], v[186:189], v[194:197], v[16:19]
	v_mfma_f32_16x16x32_bf16 v[16:19], v[146:149], v[198:201], v[44:47]
	v_mfma_f32_16x16x32_bf16 v[44:47], v[150:153], v[202:205], v[16:19]
	v_mfma_f32_16x16x32_bf16 v[16:19], v[182:185], v[198:201], v[40:43]
	v_mfma_f32_16x16x32_bf16 v[40:43], v[186:189], v[202:205], v[16:19]
	v_mfma_f32_16x16x32_bf16 v[16:19], v[146:149], v[222:225], v[28:31]
	v_mfma_f32_16x16x32_bf16 v[28:31], v[150:153], v[226:229], v[16:19]
	v_mfma_f32_16x16x32_bf16 v[16:19], v[182:185], v[222:225], v[24:27]
	v_mfma_f32_16x16x32_bf16 v[12:15], v[146:149], v[230:233], v[12:15]
	v_mfma_f32_16x16x32_bf16 v[8:11], v[182:185], v[230:233], v[8:11]
	v_mfma_f32_16x16x32_bf16 v[24:27], v[186:189], v[226:229], v[16:19]
	v_mfma_f32_16x16x32_bf16 v[12:15], v[150:153], v[234:237], v[12:15]
	v_mfma_f32_16x16x32_bf16 v[8:11], v[186:189], v[234:237], v[8:11]
	s_setprio 0
	s_barrier
	s_add_i32 s33, 0, 0x1c000
	ds_read_b128 v[16:19], v253 offset:32768
	ds_read_b128 v[20:23], v253 offset:33792
	ds_read_b128 v[138:141], v253 offset:34816
	ds_read_b128 v[142:145], v253 offset:35840
	ds_read_b128 v[146:149], v253 offset:49152
	ds_read_b128 v[150:153], v253 offset:50176
	ds_read_b128 v[182:185], v253 offset:51200
	ds_read_b128 v[186:189], v253 offset:52224
	s_add_u32 s14, s14, 0x40000
	s_addc_u32 s15, s15, 0
	s_mov_b32 m0, s92
	ds_read_b128 v[190:193], v221 offset:32768
	ds_read_b128 v[194:197], v221 offset:33792
	ds_read_b128 v[198:201], v221 offset:34816
	ds_read_b128 v[202:205], v221 offset:35840
	ds_read_b128 v[222:225], v221 offset:36864
	ds_read_b128 v[226:229], v221 offset:37888
	ds_read_b128 v[230:233], v221 offset:38912
	ds_read_b128 v[234:237], v221 offset:39936
	global_load_lds_dwordx4 v154, s[14:15]
	s_mov_b32 m0, s93
	s_nop 0
	global_load_lds_dwordx4 v158, s[14:15]
	s_waitcnt vmcnt(8)
	s_waitcnt lgkmcnt(0)
	s_barrier
	s_setprio 1
	s_waitcnt lgkmcnt(0)
	v_mfma_f32_16x16x32_bf16 v[134:137], v[16:19], v[190:193], v[134:137]
	v_mfma_f32_16x16x32_bf16 v[130:133], v[138:141], v[190:193], v[130:133]
	v_mfma_f32_16x16x32_bf16 v[118:121], v[16:19], v[198:201], v[118:121]
	v_mfma_f32_16x16x32_bf16 v[114:117], v[138:141], v[198:201], v[114:117]
	v_mfma_f32_16x16x32_bf16 v[102:105], v[16:19], v[222:225], v[102:105]
	v_mfma_f32_16x16x32_bf16 v[98:101], v[138:141], v[222:225], v[98:101]
	v_mfma_f32_16x16x32_bf16 v[84:87], v[16:19], v[230:233], v[84:87]
	v_mfma_f32_16x16x32_bf16 v[80:83], v[138:141], v[230:233], v[80:83]
	v_mfma_f32_16x16x32_bf16 v[134:137], v[20:23], v[194:197], v[134:137]
	v_mfma_f32_16x16x32_bf16 v[130:133], v[142:145], v[194:197], v[130:133]
	v_mfma_f32_16x16x32_bf16 v[118:121], v[20:23], v[202:205], v[118:121]
	v_mfma_f32_16x16x32_bf16 v[114:117], v[142:145], v[202:205], v[114:117]
	v_mfma_f32_16x16x32_bf16 v[102:105], v[20:23], v[226:229], v[102:105]
	v_mfma_f32_16x16x32_bf16 v[98:101], v[142:145], v[226:229], v[98:101]
	v_mfma_f32_16x16x32_bf16 v[84:87], v[20:23], v[234:237], v[84:87]
	v_mfma_f32_16x16x32_bf16 v[80:83], v[142:145], v[234:237], v[80:83]
	s_setprio 0
	s_setprio 1
	v_mfma_f32_16x16x32_bf16 v[126:129], v[146:149], v[190:193], v[126:129]
	v_mfma_f32_16x16x32_bf16 v[122:125], v[182:185], v[190:193], v[122:125]
	v_mfma_f32_16x16x32_bf16 v[110:113], v[146:149], v[198:201], v[110:113]
	v_mfma_f32_16x16x32_bf16 v[106:109], v[182:185], v[198:201], v[106:109]
	v_mfma_f32_16x16x32_bf16 v[92:95], v[146:149], v[222:225], v[92:95]
	v_mfma_f32_16x16x32_bf16 v[88:91], v[182:185], v[222:225], v[88:91]
	v_mfma_f32_16x16x32_bf16 v[76:79], v[146:149], v[230:233], v[76:79]
	v_mfma_f32_16x16x32_bf16 v[72:75], v[182:185], v[230:233], v[72:75]
	v_mfma_f32_16x16x32_bf16 v[126:129], v[150:153], v[194:197], v[126:129]
	v_mfma_f32_16x16x32_bf16 v[122:125], v[186:189], v[194:197], v[122:125]
	v_mfma_f32_16x16x32_bf16 v[110:113], v[150:153], v[202:205], v[110:113]
	v_mfma_f32_16x16x32_bf16 v[106:109], v[186:189], v[202:205], v[106:109]
	v_mfma_f32_16x16x32_bf16 v[92:95], v[150:153], v[226:229], v[92:95]
	v_mfma_f32_16x16x32_bf16 v[88:91], v[186:189], v[226:229], v[88:91]
	v_mfma_f32_16x16x32_bf16 v[76:79], v[150:153], v[234:237], v[76:79]
	v_mfma_f32_16x16x32_bf16 v[72:75], v[186:189], v[234:237], v[72:75]
	s_setprio 0
	s_barrier
	s_add_i32 s14, s67, s78
	s_add_i32 m0, s14, 0xffffff80
	ds_read_b128 v[190:193], v221 offset:49152
	ds_read_b128 v[194:197], v221 offset:50176
	ds_read_b128 v[198:201], v221 offset:51200
	ds_read_b128 v[202:205], v221 offset:52224
	ds_read_b128 v[222:225], v221 offset:53248
	ds_read_b128 v[226:229], v221 offset:54272
	ds_read_b128 v[230:233], v221 offset:55296
	ds_read_b128 v[234:237], v221 offset:56320
	global_load_lds_dwordx4 v156, s[12:13] offset:128
	s_add_i32 m0, s14, 0x1f80
	s_add_i32 s14, s33, s78
	global_load_lds_dwordx4 v160, s[12:13] offset:128
	s_add_u32 s12, s12, 0x10080
	s_addc_u32 s13, s13, 0
	s_mov_b32 m0, s14
	s_nop 0
	global_load_lds_dwordx4 v156, s[12:13]
	s_add_i32 m0, s14, 0x2000
	s_nop 0
	global_load_lds_dwordx4 v160, s[12:13]
	s_add_i32 m0, s21, 0xffffff80
	s_nop 0
	global_load_lds_dwordx4 v154, s[42:43] offset:128
	s_add_i32 m0, s61, 0xffffff80
	s_nop 0
	global_load_lds_dwordx4 v158, s[42:43] offset:128
	s_waitcnt vmcnt(8)
	s_waitcnt lgkmcnt(0)
	s_barrier
	s_setprio 1
	s_waitcnt lgkmcnt(0)
	v_mfma_f32_16x16x32_bf16 v[68:71], v[16:19], v[190:193], v[68:71]
	v_mfma_f32_16x16x32_bf16 v[52:55], v[16:19], v[198:201], v[52:55]
	v_mfma_f32_16x16x32_bf16 v[36:39], v[16:19], v[222:225], v[36:39]
	v_mfma_f32_16x16x32_bf16 v[0:3], v[16:19], v[230:233], v[0:3]
	v_mfma_f32_16x16x32_bf16 v[68:71], v[20:23], v[194:197], v[68:71]
	v_mfma_f32_16x16x32_bf16 v[64:67], v[138:141], v[190:193], v[64:67]
	v_mfma_f32_16x16x32_bf16 v[52:55], v[20:23], v[202:205], v[52:55]
	v_mfma_f32_16x16x32_bf16 v[48:51], v[138:141], v[198:201], v[48:51]
	v_mfma_f32_16x16x32_bf16 v[36:39], v[20:23], v[226:229], v[36:39]
	v_mfma_f32_16x16x32_bf16 v[32:35], v[138:141], v[222:225], v[32:35]
	v_mfma_f32_16x16x32_bf16 v[20:23], v[20:23], v[234:237], v[0:3]
	v_mfma_f32_16x16x32_bf16 v[0:3], v[138:141], v[230:233], v[4:7]
	v_mfma_f32_16x16x32_bf16 v[64:67], v[142:145], v[194:197], v[64:67]
	v_mfma_f32_16x16x32_bf16 v[48:51], v[142:145], v[202:205], v[48:51]
	v_mfma_f32_16x16x32_bf16 v[32:35], v[142:145], v[226:229], v[32:35]
	v_mfma_f32_16x16x32_bf16 v[16:19], v[142:145], v[234:237], v[0:3]
	s_setprio 0
	s_setprio 1
	v_mfma_f32_16x16x32_bf16 v[0:3], v[146:149], v[190:193], v[60:63]
	v_mfma_f32_16x16x32_bf16 v[60:63], v[150:153], v[194:197], v[0:3]
	v_mfma_f32_16x16x32_bf16 v[0:3], v[182:185], v[190:193], v[56:59]
	v_mfma_f32_16x16x32_bf16 v[56:59], v[186:189], v[194:197], v[0:3]
	v_mfma_f32_16x16x32_bf16 v[0:3], v[146:149], v[198:201], v[44:47]
	v_mfma_f32_16x16x32_bf16 v[44:47], v[150:153], v[202:205], v[0:3]
	v_mfma_f32_16x16x32_bf16 v[0:3], v[182:185], v[198:201], v[40:43]
	v_mfma_f32_16x16x32_bf16 v[40:43], v[186:189], v[202:205], v[0:3]
	v_mfma_f32_16x16x32_bf16 v[0:3], v[146:149], v[222:225], v[28:31]
	v_mfma_f32_16x16x32_bf16 v[28:31], v[150:153], v[226:229], v[0:3]
	v_mfma_f32_16x16x32_bf16 v[0:3], v[182:185], v[222:225], v[24:27]
	v_mfma_f32_16x16x32_bf16 v[24:27], v[186:189], v[226:229], v[0:3]
	v_mfma_f32_16x16x32_bf16 v[0:3], v[146:149], v[230:233], v[12:15]
	v_mfma_f32_16x16x32_bf16 v[12:15], v[150:153], v[234:237], v[0:3]
	v_mfma_f32_16x16x32_bf16 v[0:3], v[182:185], v[230:233], v[8:11]
	v_mfma_f32_16x16x32_bf16 v[8:11], v[186:189], v[234:237], v[0:3]
	s_setprio 0
	s_add_i32 s27, s27, 2
	s_add_u32 s4, s4, 0x100
	s_addc_u32 s5, s5, 0
	s_add_u32 s19, s19, 0x100
	s_addc_u32 s26, s26, 0
	s_cmp_gt_u32 s27, 13
	s_barrier
	s_cbranch_scc0 .LBB0_750
	v_readlane_b32 s4, v252, 30
	v_readlane_b32 s5, v252, 31
	s_and_b64 vcc, exec, s[4:5]
	s_cbranch_vccz .LBB0_753
	s_barrier
